# delta preprocess: small first-group LDS reads issued before the five raw-row reads, exact counted lgkmcnt waits
# baseline (speedup 1.0000x reference)
; __device__ __forceinline__ float bflo(unsigned u) { return __uint_as_float(u << 16); }
; __device__ __forceinline__ float bfhi(unsigned u) { return __uint_as_float(u & 0xffff0000u); }
; template <int N, int RS>
; __device__ __forceinline__ void convN(const bf16_t* rawb, const float (&w)[4][N], int tt, int off, float (&x)[N]) {
;     ...
;     if (N == 8) { const uint4 rv = *(const uint4*)(rawb + (tt + j) * RS + off); unpack8(rv, xv); }
;     else if (N == 4) { const uint2 rv = *(const uint2*)(rawb + (tt + j) * RS + off); xv[0] = bflo(rv.x); xv[1] = bfhi(rv.x); xv[2 % N] = bflo(rv.y); xv[3 % N] = bfhi(rv.y); }
;     else { const unsigned rv = *(const unsigned*)(rawb + (tt + j) * RS + off); xv[0] = bflo(rv); xv[1] = bfhi(rv); }
; #pragma unroll
;     for (int i = 0; i < N; ++i) x[i] += w[j][i] * xv[i];
; template <int MIX>
; __device__ __forceinline__ void scan_part(const Params& p, const int layer, const int smp, const int b0, const int bstep, const int bend, const int h, const int part, char* lds, const int tid) {
;     ...
;       if (valid) {
;         float xq[8], xk[8], xv[VN];
;         { float cwv[4][VN];
; #pragma unroll
;           for (int j = 0; j < 4; ++j)
; #pragma unroll
;             for (int i = 0; i < VN; ++i) cwv[j][i] = cwl[j * RS + 128 + sub * VN + i];
;           convN<VN, RS>(rawb, cwv, tt, 128 + sub * VN, xv); }
;         convN<8, RS>(rawb, cwq, tt, sub * 8, xq);
;         convN<8, RS>(rawb, cwk, tt, 64 + sub * 8, xk);
.Ld_top_done:
	s_and_saveexec_b64 s[50:51], s[42:43]
	s_cbranch_execz .LBB0_426
	v_add_u32_e32 v232, s23, v131
	v_lshlrev_b32_e32 v232, 2, v232
	ds_read_b32 v230, v232 offset:50880
	v_lshlrev_b32_e32 v231, 16, v133
	v_mul_f32_e32 v231, 0xbfb8aa3b, v231
	v_add_u32_e32 v2, v140, v138
	v_add_u32_e32 v0, 0x9200, v2
	v_add_u32_e32 v216, 0xbc00, v137
	v_exp_f32_e32 v231, v231
	ds_read2_b32 v[0:1], v0 offset0:64 offset1:136
	ds_read2_b64 v[216:219], v216 offset0:120 offset1:192
	v_add_u32_e32 v220, 0xc000, v137
	v_add_u32_e32 v2, 0x9400, v2
	v_add_f32_e32 v231, 1.0, v231
	ds_read2_b64 v[220:223], v220 offset0:136 offset1:208
	ds_read_b128 v[78:81], v151 offset:37376
	ds_read_b128 v[82:85], v151 offset:37504
	ds_read_b128 v[86:89], v151 offset:37664
	ds_read_b128 v[90:93], v151 offset:37952
	ds_read_b128 v[174:177], v151 offset:38240
	s_waitcnt lgkmcnt(7)
	v_lshlrev_b32_e32 v225, 16, v1
	v_lshlrev_b32_e32 v224, 16, v0
	v_rcp_f32_e32 v231, v231
	s_waitcnt lgkmcnt(6)
	v_mov_b32_e32 v226, v216
	v_mov_b32_e32 v227, v218
	v_pk_mul_f32 v[224:225], v[226:227], v[224:225]
	v_and_b32_e32 v1, 0xffff0000, v1
	v_add_f32_e32 v216, 0, v224
	v_add_f32_e32 v226, v216, v225
	ds_read2_b32 v[224:225], v2 offset0:80 offset1:152
	v_and_b32_e32 v0, 0xffff0000, v0
	v_mov_b32_e32 v218, v217
	v_pk_mul_f32 v[0:1], v[218:219], v[0:1]
	s_waitcnt lgkmcnt(6)
	v_mov_b32_e32 v216, v220
	v_add_f32_e32 v0, 0, v0
	v_add_f32_e32 v2, v0, v1
	s_waitcnt lgkmcnt(0)
	v_lshlrev_b32_e32 v1, 16, v225
	v_lshlrev_b32_e32 v0, 16, v224
	v_mov_b32_e32 v217, v222
	v_pk_mul_f32 v[0:1], v[216:217], v[0:1]
	v_and_b32_e32 v217, 0xffff0000, v225
	v_and_b32_e32 v216, 0xffff0000, v224
	v_mov_b32_e32 v222, v221
	v_add_f32_e32 v0, v226, v0
	v_pk_mul_f32 v[216:217], v[222:223], v[216:217]
	v_add_f32_e32 v0, v0, v1
	v_add_f32_e32 v1, v2, v216
	v_add_f32_e32 v1, v1, v217
	v_mul_f32_e32 v2, 0xbfb8aa3b, v0
	v_exp_f32_e32 v2, v2
	v_mul_f32_e32 v76, 0xbfb8aa3b, v1
	v_exp_f32_e32 v77, v76
	s_waitcnt lgkmcnt(4)
	v_lshlrev_b32_e32 v154, 16, v80
	v_and_b32_e32 v155, 0xffff0000, v80
	v_lshlrev_b32_e32 v94, 16, v78
	v_and_b32_e32 v95, 0xffff0000, v78
	v_lshlrev_b32_e32 v106, 16, v79
	v_and_b32_e32 v107, 0xffff0000, v79
	v_lshlrev_b32_e32 v178, 16, v81
	v_and_b32_e32 v179, 0xffff0000, v81
	ds_read_b128 v[78:81], v151 offset:37792
	s_waitcnt lgkmcnt(3)
	v_lshlrev_b32_e32 v180, 16, v86
	v_and_b32_e32 v181, 0xffff0000, v86
	v_lshlrev_b32_e32 v182, 16, v87
	v_and_b32_e32 v183, 0xffff0000, v87
	v_lshlrev_b32_e32 v184, 16, v88
	v_and_b32_e32 v185, 0xffff0000, v88
	v_lshlrev_b32_e32 v186, 16, v89
	v_and_b32_e32 v187, 0xffff0000, v89
	ds_read_b128 v[86:89], v151 offset:38080
	s_waitcnt lgkmcnt(3)
	v_lshlrev_b32_e32 v188, 16, v90
	v_and_b32_e32 v189, 0xffff0000, v90
	v_lshlrev_b32_e32 v190, 16, v91
	v_and_b32_e32 v191, 0xffff0000, v91
	v_lshlrev_b32_e32 v192, 16, v92
	v_and_b32_e32 v193, 0xffff0000, v92
	v_lshlrev_b32_e32 v194, 16, v93
	v_and_b32_e32 v195, 0xffff0000, v93
	ds_read_b128 v[90:93], v151 offset:38368
	s_waitcnt vmcnt(2)
	v_pk_fma_f32 v[154:155], v[4:5], v[154:155], 0 op_sel_hi:[1,1,0]
	v_add_f32_e32 v2, 1.0, v2
	s_waitcnt vmcnt(2)
	v_pk_fma_f32 v[154:155], v[12:13], v[184:185], v[154:155]
	s_waitcnt lgkmcnt(3)
	v_lshlrev_b32_e32 v198, 16, v176
	v_and_b32_e32 v199, 0xffff0000, v176
	s_waitcnt vmcnt(2)
	v_pk_fma_f32 v[154:155], v[20:21], v[192:193], v[154:155]
	v_rcp_f32_e32 v76, v2
	v_add_f32_e32 v2, 1.0, v77
	s_waitcnt vmcnt(2)
	v_pk_fma_f32 v[154:155], v[28:29], v[198:199], v[154:155]
	v_rcp_f32_e32 v77, v2
	v_mul_f32_e32 v2, 0xbfb8aa3b, v154
	v_lshlrev_b32_e32 v202, 16, v84
	v_and_b32_e32 v203, 0xffff0000, v84
	s_waitcnt lgkmcnt(0)
	v_lshlrev_b32_e32 v214, 16, v92
	v_and_b32_e32 v215, 0xffff0000, v92
	v_exp_f32_e32 v2, v2
	v_mul_f32_e32 v92, 0xbfb8aa3b, v155
	v_lshlrev_b32_e32 v206, 16, v80
	v_and_b32_e32 v207, 0xffff0000, v80
	v_exp_f32_e32 v158, v92
	s_waitcnt vmcnt(2)
	v_pk_fma_f32 v[192:193], v[36:37], v[202:203], 0 op_sel_hi:[1,1,0]
	v_lshlrev_b32_e32 v210, 16, v88
	v_and_b32_e32 v211, 0xffff0000, v88
	s_waitcnt vmcnt(2)
	v_pk_fma_f32 v[192:193], v[44:45], v[206:207], v[192:193]
	v_add_f32_e32 v2, 1.0, v2
	s_waitcnt vmcnt(2)
	v_pk_fma_f32 v[192:193], v[52:53], v[210:211], v[192:193]
	v_rcp_f32_e32 v184, v2
	s_waitcnt vmcnt(2)
; __device__ __forceinline__ float bflo(unsigned u) { return __uint_as_float(u << 16); }
; __device__ __forceinline__ float bfhi(unsigned u) { return __uint_as_float(u & 0xffff0000u); }
; __device__ __forceinline__ float siluf_(float x) { return x * __builtin_amdgcn_rcpf(1.0f + __expf(-x)); }
; template <int N, int RS>
; __device__ __forceinline__ void convN(const bf16_t* rawb, const float (&w)[4][N], int tt, int off, float (&x)[N]) {
; #pragma unroll
;   for (int i = 0; i < N; ++i) x[i] = 0.f;
; #pragma unroll
;   for (int j = 0; j < 4; ++j) {
;     float xv[N];
;     if (N == 8) { const uint4 rv = *(const uint4*)(rawb + (tt + j) * RS + off); unpack8(rv, xv); }
;     else if (N == 4) { const uint2 rv = *(const uint2*)(rawb + (tt + j) * RS + off); xv[0] = bflo(rv.x); xv[1] = bfhi(rv.x); xv[2 % N] = bflo(rv.y); xv[3 % N] = bfhi(rv.y); }
;     else { const unsigned rv = *(const unsigned*)(rawb + (tt + j) * RS + off); xv[0] = bflo(rv); xv[1] = bfhi(rv); }
; #pragma unroll
;     for (int i = 0; i < N; ++i) x[i] += w[j][i] * xv[i];
;   }
;   if (N == 2) {
; #pragma unroll
;     for (int i = 0; i < N; ++i) asm volatile("" : "+v"(x[i]));
;   }
; #pragma unroll
;   for (int i = 0; i < N; ++i) x[i] = siluf_(x[i]);
; template <int MIX>
; __device__ __forceinline__ void scan_part(const Params& p, const int layer, const int smp, const int b0, const int bstep, const int bend, const int h, const int part, char* lds, const int tid) {
;     ...
;         convN<8, RS>(rawb, cwq, tt, sub * 8, xq);
;         convN<8, RS>(rawb, cwk, tt, 64 + sub * 8, xk);
	v_pk_fma_f32 v[192:193], v[60:61], v[214:215], v[192:193]
	v_add_f32_e32 v2, 1.0, v158
	v_mul_f32_e32 v158, 0xbfb8aa3b, v192
	v_exp_f32_e32 v158, v158
	v_mul_f32_e32 v159, 0xbfb8aa3b, v193
	v_exp_f32_e32 v159, v159
	v_pk_fma_f32 v[178:179], v[6:7], v[178:179], 0 op_sel_hi:[1,1,0]
	v_lshlrev_b32_e32 v176, 16, v177
	v_pk_fma_f32 v[178:179], v[14:15], v[186:187], v[178:179]
	v_and_b32_e32 v177, 0xffff0000, v177
	v_rcp_f32_e32 v185, v2
	v_add_f32_e32 v2, 1.0, v158
	v_pk_fma_f32 v[178:179], v[22:23], v[194:195], v[178:179]
	v_rcp_f32_e32 v198, v2
	v_add_f32_e32 v2, 1.0, v159
	v_pk_fma_f32 v[176:177], v[30:31], v[176:177], v[178:179]
	v_rcp_f32_e32 v199, v2
	v_mul_f32_e32 v2, 0xbfb8aa3b, v176
	v_exp_f32_e32 v2, v2
	v_mul_f32_e32 v158, 0xbfb8aa3b, v177
	v_exp_f32_e32 v158, v158
	v_pk_fma_f32 v[94:95], v[8:9], v[94:95], 0 op_sel_hi:[1,1,0]
	v_lshlrev_b32_e32 v196, 16, v174
	v_pk_fma_f32 v[94:95], v[16:17], v[180:181], v[94:95]
	v_and_b32_e32 v197, 0xffff0000, v174
	v_add_f32_e32 v2, 1.0, v2
	v_pk_fma_f32 v[94:95], v[24:25], v[188:189], v[94:95]
	v_rcp_f32_e32 v186, v2
	v_add_f32_e32 v2, 1.0, v158
	v_pk_fma_f32 v[94:95], v[32:33], v[196:197], v[94:95]
	v_rcp_f32_e32 v187, v2
	v_mul_f32_e32 v2, 0xbfb8aa3b, v94
	v_exp_f32_e32 v2, v2
	v_mul_f32_e32 v158, 0xbfb8aa3b, v95
	v_exp_f32_e32 v158, v158
	v_pk_fma_f32 v[106:107], v[10:11], v[106:107], 0 op_sel_hi:[1,1,0]
	v_lshlrev_b32_e32 v174, 16, v175
	v_pk_fma_f32 v[106:107], v[18:19], v[182:183], v[106:107]
	v_and_b32_e32 v175, 0xffff0000, v175
	v_pk_fma_f32 v[106:107], v[26:27], v[190:191], v[106:107]
	v_add_f32_e32 v2, 1.0, v2
	v_pk_fma_f32 v[106:107], v[34:35], v[174:175], v[106:107]
	v_rcp_f32_e32 v180, v2
	v_add_f32_e32 v2, 1.0, v158
	v_mul_f32_e32 v158, 0xbfb8aa3b, v106
	v_exp_f32_e32 v158, v158
	v_mul_f32_e32 v159, 0xbfb8aa3b, v107
	v_lshlrev_b32_e32 v84, 16, v85
	v_and_b32_e32 v85, 0xffff0000, v85
	v_exp_f32_e32 v159, v159
	v_lshlrev_b32_e32 v80, 16, v81
	v_and_b32_e32 v81, 0xffff0000, v81
	v_pk_fma_f32 v[84:85], v[38:39], v[84:85], 0 op_sel_hi:[1,1,0]
	v_lshlrev_b32_e32 v88, 16, v89
	v_and_b32_e32 v89, 0xffff0000, v89
	v_pk_fma_f32 v[80:81], v[46:47], v[80:81], v[84:85]
	v_lshlrev_b32_e32 v92, 16, v93
	v_and_b32_e32 v93, 0xffff0000, v93
	v_rcp_f32_e32 v181, v2
	v_add_f32_e32 v2, 1.0, v158
	v_pk_fma_f32 v[80:81], v[54:55], v[88:89], v[80:81]
	v_rcp_f32_e32 v174, v2
	v_add_f32_e32 v2, 1.0, v159
	v_pk_fma_f32 v[80:81], v[62:63], v[92:93], v[80:81]
	v_rcp_f32_e32 v175, v2
	v_mul_f32_e32 v2, 0xbfb8aa3b, v80
	v_exp_f32_e32 v2, v2
	v_mul_f32_e32 v84, 0xbfb8aa3b, v81
	v_exp_f32_e32 v89, v84
	v_lshlrev_b32_e32 v200, 16, v82
	v_and_b32_e32 v201, 0xffff0000, v82
	v_lshlrev_b32_e32 v204, 16, v78
	v_and_b32_e32 v205, 0xffff0000, v78
	v_add_f32_e32 v2, 1.0, v2
	v_pk_fma_f32 v[92:93], v[40:41], v[200:201], 0 op_sel_hi:[1,1,0]
	v_lshlrev_b32_e32 v82, 16, v83
	v_and_b32_e32 v83, 0xffff0000, v83
	v_lshlrev_b32_e32 v208, 16, v86
	v_and_b32_e32 v209, 0xffff0000, v86
	v_rcp_f32_e32 v88, v2
	v_add_f32_e32 v2, 1.0, v89
	v_pk_fma_f32 v[92:93], v[48:49], v[204:205], v[92:93]
	v_lshlrev_b32_e32 v78, 16, v79
	v_and_b32_e32 v79, 0xffff0000, v79
	v_lshlrev_b32_e32 v212, 16, v90
	v_and_b32_e32 v213, 0xffff0000, v90
	v_rcp_f32_e32 v89, v2
	v_pk_fma_f32 v[92:93], v[56:57], v[208:209], v[92:93]
	v_pk_fma_f32 v[82:83], v[42:43], v[82:83], 0 op_sel_hi:[1,1,0]
	v_lshlrev_b32_e32 v86, 16, v87
	v_and_b32_e32 v87, 0xffff0000, v87
	s_waitcnt vmcnt(2)
; __device__ __forceinline__ float bflo(unsigned u) { return __uint_as_float(u << 16); }
; __device__ __forceinline__ float sigmoidf_(float x) { return __builtin_amdgcn_rcpf(1.0f + __expf(-x)); }
; __device__ __forceinline__ float softplusf_(float x) { return fmaxf(x, 0.f) + __logf(1.0f + __expf(-fabsf(x))); }
; __device__ __forceinline__ float red8d(float x) { x += dpp_x1(x); x += dpp_x2(x); x += dpp_hm(x); return x; }
; template <int MIX>
; __device__ __forceinline__ void scan_part(const Params& p, const int layer, const int smp, const int b0, const int bstep, const int bend, const int h, const int part, char* lds, const int tid) {
;     ...
; #pragma unroll
;         for (int i = 0; i < VN; ++i) dst[192 + sub * VN + i] = xv[i];
;         float ssq = 0.f, ssk = 0.f;
; #pragma unroll
;         for (int i = 0; i < 8; ++i) { ssq += xq[i] * xq[i]; ssk += xk[i] * xk[i]; }
;         ssq = red8d(ssq); ssk = red8d(ssk);
;         const float rq = rsqrtf(ssq + 1e-6f) * 0.125f, rk = rsqrtf(ssk + 1e-6f);
;         float qk = 0.f;
; #pragma unroll
;         for (int i = 0; i < 8; ++i) { xq[i] *= rq; xk[i] *= rk; qk += xq[i] * xk[i]; }
;         qk = red8d(qk);
;         *(f32x4*)(dst + sub * 8) = (f32x4){xq[0], xq[1], xq[2], xq[3]}; *(f32x4*)(dst + sub * 8 + 4) = (f32x4){xq[4], xq[5], xq[6], xq[7]};
;         *(f32x4*)(dst + 64 + sub * 8) = (f32x4){xk[0], xk[1], xk[2], xk[3]}; *(f32x4*)(dst + 64 + sub * 8 + 4) = (f32x4){xk[4], xk[5], xk[6], xk[7]};
;         if (sub == 0) {
;           const float be = sigmoidf_(bflo(ex0)), al = bflo(ex1);
;           const float a = __expf(-Aexp * softplusf_(al + dtb));
;           *(f32x4*)(scal + tt * 4) = (f32x4){a, be, qk, 0.f};
;         }
	v_pk_fma_f32 v[92:93], v[64:65], v[212:213], v[92:93]
	v_pk_fma_f32 v[78:79], v[50:51], v[78:79], v[82:83]
	v_lshlrev_b32_e32 v90, 16, v91
	v_and_b32_e32 v91, 0xffff0000, v91
	v_mul_f32_e32 v2, 0xbfb8aa3b, v92
	v_pk_fma_f32 v[78:79], v[58:59], v[86:87], v[78:79]
	v_exp_f32_e32 v2, v2
	v_mul_f32_e32 v158, 0xbfb8aa3b, v93
	v_pk_fma_f32 v[78:79], v[66:67], v[90:91], v[78:79]
	v_pk_mul_f32 v[106:107], v[106:107], v[174:175]
	v_exp_f32_e32 v158, v158
	v_pk_mul_f32 v[174:175], v[80:81], v[88:89]
	v_mul_f32_e32 v81, 0xbfb8aa3b, v78
	v_exp_f32_e32 v82, v81
	v_mul_f32_e32 v81, 0xbfb8aa3b, v79
	v_exp_f32_e32 v83, v81
	v_add_f32_e32 v2, 1.0, v2
	v_rcp_f32_e32 v80, v2
	v_add_f32_e32 v2, 1.0, v158
	v_rcp_f32_e32 v81, v2
	v_add_f32_e32 v2, 1.0, v82
	v_rcp_f32_e32 v82, v2
	v_add_f32_e32 v2, 1.0, v83
	v_rcp_f32_e32 v83, v2
	v_pk_mul_f32 v[94:95], v[94:95], v[180:181]
	v_pk_mul_f32 v[88:89], v[92:93], v[80:81]
	v_pk_mul_f32 v[180:181], v[94:95], v[94:95]
	v_pk_mul_f32 v[80:81], v[88:89], v[88:89]
	v_pk_mul_f32 v[90:91], v[78:79], v[82:83]
	v_pk_mul_f32 v[84:85], v[106:107], v[106:107]
	v_pk_mul_f32 v[78:79], v[90:91], v[90:91]
	v_mov_b32_e32 v82, v80
	v_mov_b32_e32 v83, v180
	v_mov_b32_e32 v180, v81
	v_pk_mul_f32 v[154:155], v[154:155], v[184:185]
	v_pk_mul_f32 v[192:193], v[192:193], v[198:199]
	v_pk_add_f32 v[80:81], v[82:83], v[180:181]
	v_mov_b32_e32 v82, v78
	v_mov_b32_e32 v83, v84
	v_pk_mul_f32 v[184:185], v[154:155], v[154:155]
	v_pk_mul_f32 v[178:179], v[192:193], v[192:193]
	v_pk_add_f32 v[80:81], v[80:81], v[82:83]
	v_mov_b32_e32 v84, v79
	v_pk_mul_f32 v[176:177], v[176:177], v[186:187]
	v_pk_add_f32 v[78:79], v[84:85], v[80:81]
	v_mov_b32_e32 v80, v178
	v_mov_b32_e32 v81, v184
	v_pk_mul_f32 v[182:183], v[176:177], v[176:177]
	v_pk_mul_f32 v[86:87], v[174:175], v[174:175]
	v_pk_add_f32 v[78:79], v[80:81], v[78:79]
	v_mov_b32_e32 v184, v179
	v_pk_add_f32 v[78:79], v[184:185], v[78:79]
	v_mov_b32_e32 v80, v86
	v_mov_b32_e32 v81, v182
	v_pk_add_f32 v[78:79], v[80:81], v[78:79]
	v_mov_b32_e32 v182, v87
	v_pk_add_f32 v[78:79], v[182:183], v[78:79]
	s_mov_b32 s44, 0x358637bd
	v_pk_mul_f32 v[0:1], v[0:1], v[76:77]
	v_mov_b32_dpp v81, v79 quad_perm:[1,0,3,2] row_mask:0xf bank_mask:0xf bound_ctrl:1
	v_mov_b32_dpp v80, v78 quad_perm:[1,0,3,2] row_mask:0xf bank_mask:0xf bound_ctrl:1
	v_pk_add_f32 v[78:79], v[78:79], v[80:81]
	ds_write_b64 v141, v[0:1] offset:768
	s_nop 0
	v_mov_b32_dpp v81, v79 quad_perm:[2,3,0,1] row_mask:0xf bank_mask:0xf bound_ctrl:1
	v_mov_b32_dpp v80, v78 quad_perm:[2,3,0,1] row_mask:0xf bank_mask:0xf bound_ctrl:1
	v_pk_add_f32 v[78:79], v[78:79], v[80:81]
	s_nop 1
	v_mov_b32_dpp v81, v79 row_half_mirror row_mask:0xf bank_mask:0xf bound_ctrl:1
	v_mov_b32_dpp v80, v78 row_half_mirror row_mask:0xf bank_mask:0xf bound_ctrl:1
	v_pk_add_f32 v[78:79], v[78:79], v[80:81]
	s_nop 0
	v_pk_add_f32 v[78:79], v[78:79], s[44:45] op_sel_hi:[1,0]
	s_nop 0
	v_mul_f32_e32 v2, 0x4b800000, v79
	v_cmp_gt_f32_e32 vcc, s92, v79
	s_nop 1
	v_cndmask_b32_e32 v2, v79, v2, vcc
	v_rsq_f32_e32 v2, v2
	s_nop 0
	v_mul_f32_e32 v0, 0x45800000, v2
	v_cndmask_b32_e32 v0, v2, v0, vcc
	v_mul_f32_e32 v0, 0x3e000000, v0
	v_pk_mul_f32 v[76:77], v[94:95], v[0:1] op_sel_hi:[1,0]
	v_mul_f32_e32 v1, 0x4b800000, v78
	v_cmp_gt_f32_e32 vcc, s92, v78
	s_nop 1
	v_cndmask_b32_e32 v1, v78, v1, vcc
	v_rsq_f32_e32 v1, v1
	s_nop 0
	v_pk_mul_f32 v[78:79], v[106:107], v[0:1] op_sel_hi:[1,0]
	v_pk_mul_f32 v[80:81], v[154:155], v[0:1] op_sel_hi:[1,0]
	v_pk_mul_f32 v[82:83], v[176:177], v[0:1] op_sel_hi:[1,0]
	v_mul_f32_e32 v0, 0x45800000, v1
	v_cndmask_b32_e32 v0, v1, v0, vcc
	v_pk_mul_f32 v[84:85], v[88:89], v[0:1] op_sel_hi:[1,0]
	s_nop 0
	v_pk_mul_f32 v[86:87], v[90:91], v[0:1] op_sel_hi:[1,0]
	s_nop 0
	v_pk_mul_f32 v[88:89], v[192:193], v[0:1] op_sel_hi:[1,0]
	s_nop 0
	v_pk_mul_f32 v[90:91], v[174:175], v[0:1] op_sel_hi:[1,0]
	ds_write_b128 v152, v[76:79]
	ds_write_b128 v152, v[80:83] offset:16
	ds_write_b128 v152, v[84:87] offset:256
	ds_write_b128 v152, v[88:91] offset:272
	s_and_b64 exec, exec, s[38:39]
	s_cbranch_execz .LBB0_426
	v_mov_b32_e32 v2, 0
	s_waitcnt lgkmcnt(5)
	v_mov_b32_e32 v0, v230
	v_mov_b32_e32 v1, v231
	ds_write_b128 v142, v[0:3] offset:36864
